# v078 + P0 weight-transpose loops rotated across waves
# baseline (speedup 1.0000x reference)
.LBB0_12:
	s_mov_b64 s[4:5], s[0:1]
	s_mov_b64 s[8:9], s[0:1]
	v_mov_b32_e32 v6, v190
	s_nop 0
	v_readfirstlane_b32 s3, v6
	s_ashr_i32 s10, s3, 6
	s_mov_b32 s3, s2
	s_lshl_b32 s3, s3, 3
	s_add_i32 s3, s3, s10
	s_cmp_eq_u32 s24, 0x100
	s_cbranch_scc0 .Lp0rot_1
	s_add_i32 s3, s3, 1024
	s_and_b32 s3, s3, 0x7ff
.Lp0rot_1:
	s_cmpk_gt_i32 s3, 0x3ff
	s_cbranch_scc1 .LBB0_17
	s_load_dwordx2 s[12:13], s[4:5], 0x10
	s_load_dwordx2 s[14:15], s[8:9], 0xe0
	v_lshlrev_b32_e32 v2, 4, v6
	v_and_b32_e32 v4, 0xf0, v2
	v_mov_b32_e32 v5, 0
	s_waitcnt lgkmcnt(0)
	v_lshl_add_u64 v[2:3], s[12:13], 0, v[4:5]
	v_lshlrev_b32_e32 v4, 3, v6
	s_mul_i32 s8, s10, 0x4100
	v_bfe_u32 v8, v6, 3, 3
	v_and_b32_e32 v4, 56, v4
	s_add_i32 s9, s8, 0
	v_mul_u32_u24_e32 v7, 0x104, v4
	v_lshlrev_b32_e32 v9, 2, v8
	v_bfe_u32 v1, v6, 4, 2
	s_mov_b64 s[4:5], 0x1000000
	s_movk_i32 s10, 0x104
	v_lshlrev_b32_e32 v4, 1, v4
	v_add3_u32 v9, s9, v7, v9
	v_mov_b32_e32 v7, s8
	v_and_b32_e32 v6, 15, v6
	v_lshl_add_u64 v[2:3], v[2:3], 0, s[4:5]
	v_lshl_add_u64 v[4:5], s[14:15], 0, v[4:5]
	s_mov_b64 s[4:5], 0x900000
	v_mad_u32_u24 v7, v1, s10, v7
	v_lshlrev_b32_e32 v6, 4, v6
	v_lshl_add_u64 v[4:5], v[4:5], 0, s[4:5]
	v_or_b32_e32 v10, 8, v8
	v_or_b32_e32 v11, 16, v8
	v_or_b32_e32 v12, 24, v8
	v_or_b32_e32 v13, 32, v8
	v_or_b32_e32 v14, 40, v8
	v_or_b32_e32 v15, 48, v8
	v_or_b32_e32 v16, 56, v8
	v_add3_u32 v17, v7, v6, 0
	v_add_u32_e32 v18, 0x400, v9

.LBB0_17:
	s_mov_b64 s[4:5], s[0:1]
	s_mov_b64 s[8:9], s[0:1]
	v_mov_b32_e32 v6, v190
	s_nop 0
	v_readfirstlane_b32 s3, v6
	s_ashr_i32 s10, s3, 6
	s_mov_b32 s3, s2
	s_lshl_b32 s3, s3, 3
	s_add_i32 s3, s3, s10
	s_cmp_eq_u32 s24, 0x100
	s_cbranch_scc0 .Lp0rot_2
	s_add_i32 s3, s3, 512
	s_and_b32 s3, s3, 0x7ff
.Lp0rot_2:
	s_cmpk_gt_i32 s3, 0x3ff
	s_cbranch_scc1 .LBB0_22
	s_load_dwordx2 s[12:13], s[4:5], 0x10
	s_load_dwordx2 s[14:15], s[8:9], 0xe0
	v_lshlrev_b32_e32 v2, 4, v6
	v_and_b32_e32 v4, 0xf0, v2
	v_mov_b32_e32 v5, 0
	s_waitcnt lgkmcnt(0)
	v_lshl_add_u64 v[2:3], s[12:13], 0, v[4:5]
	v_lshlrev_b32_e32 v4, 3, v6
	s_mul_i32 s8, s10, 0x4100
	v_bfe_u32 v8, v6, 3, 3
	v_and_b32_e32 v4, 56, v4
	s_add_i32 s9, s8, 0
	v_mul_u32_u24_e32 v7, 0x104, v4
	v_lshlrev_b32_e32 v9, 2, v8
	v_bfe_u32 v1, v6, 4, 2
	s_mov_b64 s[4:5], 0x2000000
	s_movk_i32 s10, 0x104
	v_lshlrev_b32_e32 v4, 1, v4
	v_add3_u32 v9, s9, v7, v9
	v_mov_b32_e32 v7, s8
	v_and_b32_e32 v6, 15, v6
	v_lshl_add_u64 v[2:3], v[2:3], 0, s[4:5]
	v_lshl_add_u64 v[4:5], s[14:15], 0, v[4:5]
	s_mov_b64 s[4:5], 0x1100000
	v_mad_u32_u24 v7, v1, s10, v7
	v_lshlrev_b32_e32 v6, 4, v6
	v_lshl_add_u64 v[4:5], v[4:5], 0, s[4:5]
	v_or_b32_e32 v10, 8, v8
	v_or_b32_e32 v11, 16, v8
	v_or_b32_e32 v12, 24, v8
	v_or_b32_e32 v13, 32, v8
	v_or_b32_e32 v14, 40, v8
	v_or_b32_e32 v15, 48, v8
	v_or_b32_e32 v16, 56, v8
	v_add3_u32 v17, v7, v6, 0
	v_add_u32_e32 v18, 0x400, v9

.LBB0_22:
	s_mov_b64 s[4:5], s[0:1]
	s_mov_b64 s[8:9], s[0:1]
	v_mov_b32_e32 v1, v190
	s_nop 0
	v_readfirstlane_b32 s3, v1
	s_ashr_i32 s10, s3, 6
	s_mov_b32 s3, s2
	s_lshl_b32 s3, s3, 3
	s_add_i32 s3, s3, s10
	s_cmp_eq_u32 s24, 0x100
	s_cbranch_scc0 .Lp0rot_3
	s_add_i32 s3, s3, 1536
	s_and_b32 s3, s3, 0x7ff
.Lp0rot_3:
	s_cmpk_lt_i32 s3, 0x60
	s_cbranch_scc0 .LBB0_27
	s_load_dwordx2 s[12:13], s[4:5], 0x20
	s_load_dwordx2 s[14:15], s[8:9], 0xe0
	s_mulk_i32 s10, 0x4100
	v_bfe_u32 v2, v1, 5, 1
	v_lshlrev_b32_e32 v3, 2, v1
	v_bfe_u32 v7, v1, 3, 3
	v_lshlrev_b32_e32 v1, 3, v1
	s_add_i32 s5, s10, 0
	v_and_b32_e32 v8, 0x7c, v3
	v_mov_b32_e32 v9, 0
	v_and_b32_e32 v1, 56, v1
	s_waitcnt lgkmcnt(0)
	v_lshl_add_u64 v[4:5], s[12:13], 0, v[8:9]
	v_add_u32_e32 v6, s5, v8
	v_lshlrev_b32_e32 v8, 1, v1
	v_mul_u32_u24_e32 v3, 0x84, v1
	v_lshl_add_u64 v[8:9], s[14:15], 0, v[8:9]
	s_mov_b64 s[8:9], 0x1900000
	v_lshlrev_b32_e32 v1, 2, v7
	s_movk_i32 s4, 0x84
	v_lshl_add_u64 v[8:9], v[8:9], 0, s[8:9]
	v_add3_u32 v13, s5, v3, v1
	v_or_b32_e32 v14, 8, v7
	v_or_b32_e32 v15, 16, v7
	v_or_b32_e32 v16, 24, v7
	v_mov_b32_e32 v1, v2
	s_movk_i32 s5, 0x180

.LBB0_31:
	s_mov_b64 s[4:5], s[0:1]
	s_mov_b64 s[10:11], s[0:1]
	v_mov_b32_e32 v1, v190
	s_nop 0
	v_readfirstlane_b32 s3, v1
	s_ashr_i32 s12, s3, 6
	s_mov_b32 s3, s2
	s_lshl_b32 s3, s3, 3
	s_add_i32 s3, s3, s12
	s_cmp_eq_u32 s24, 0x100
	s_cbranch_scc0 .Lp0rot_4
	s_add_i32 s3, s3, 1440
	s_and_b32 s3, s3, 0x7ff
.Lp0rot_4:
	s_cmpk_gt_i32 s3, 0x5f
	s_cbranch_scc1 .LBB0_36
	s_load_dwordx2 s[14:15], s[4:5], 0x38
	s_load_dwordx2 s[16:17], s[10:11], 0xe0
	s_mulk_i32 s12, 0x4100
	v_bfe_u32 v2, v1, 5, 1
	v_lshlrev_b32_e32 v3, 2, v1
	v_bfe_u32 v7, v1, 3, 3
	v_lshlrev_b32_e32 v1, 3, v1
	s_add_i32 s5, s12, 0
	v_and_b32_e32 v8, 0x7c, v3
	v_mov_b32_e32 v9, 0
	v_and_b32_e32 v1, 56, v1
	s_waitcnt lgkmcnt(0)
	v_lshl_add_u64 v[4:5], s[14:15], 0, v[8:9]
	v_add_u32_e32 v6, s5, v8
	v_lshlrev_b32_e32 v8, 1, v1
	v_mul_u32_u24_e32 v3, 0x84, v1
	v_lshl_add_u64 v[8:9], s[16:17], 0, v[8:9]
	s_mov_b64 s[10:11], 0x1a00000
	v_lshlrev_b32_e32 v1, 2, v7
	s_movk_i32 s4, 0x84
	v_lshl_add_u64 v[8:9], v[8:9], 0, s[10:11]
	v_add3_u32 v13, s5, v3, v1
	v_or_b32_e32 v14, 8, v7
	v_or_b32_e32 v15, 16, v7
	v_or_b32_e32 v16, 24, v7
	v_mov_b32_e32 v1, v2
	s_movk_i32 s5, 0x180

.LBB0_40:
	s_mov_b64 s[4:5], s[0:1]
	s_mov_b64 s[8:9], s[0:1]
	v_mov_b32_e32 v6, v190
	s_nop 0
	v_readfirstlane_b32 s3, v6
	s_ashr_i32 s7, s3, 6
	s_mov_b32 s3, s2
	s_lshl_b32 s3, s3, 3
	s_add_i32 s3, s3, s7
	s_cmp_eq_u32 s24, 0x100
	s_cbranch_scc0 .Lp0rot_5
	s_add_i32 s3, s3, 1344
	s_and_b32 s3, s3, 0x7ff
.Lp0rot_5:
	s_cmpk_gt_i32 s3, 0x7f
	s_cbranch_scc1 .LBB0_45
	s_load_dwordx2 s[10:11], s[4:5], 0x48
	s_load_dwordx2 s[12:13], s[8:9], 0xe0
	v_lshlrev_b32_e32 v2, 4, v6
	v_and_b32_e32 v4, 0xf0, v2
	v_mov_b32_e32 v5, 0
	s_waitcnt lgkmcnt(0)
	v_lshl_add_u64 v[2:3], s[10:11], 0, v[4:5]
	v_lshlrev_b32_e32 v4, 3, v6
	s_mulk_i32 s7, 0x4100
	v_bfe_u32 v8, v6, 3, 3
	v_and_b32_e32 v4, 56, v4
	s_add_i32 s8, s7, 0
	v_mul_u32_u24_e32 v7, 0x104, v4
	v_lshlrev_b32_e32 v9, 2, v8
	v_bfe_u32 v1, v6, 4, 2
	s_movk_i32 s9, 0x104
	v_lshlrev_b32_e32 v4, 1, v4
	v_add3_u32 v9, s8, v7, v9
	v_mov_b32_e32 v7, s7
	v_and_b32_e32 v6, 15, v6
	v_lshl_add_u64 v[4:5], s[12:13], 0, v[4:5]
	s_mov_b64 s[4:5], 0x1b00000
	v_mad_u32_u24 v7, v1, s9, v7
	v_lshlrev_b32_e32 v6, 4, v6
	v_lshl_add_u64 v[4:5], v[4:5], 0, s[4:5]
	v_or_b32_e32 v10, 8, v8
	v_or_b32_e32 v11, 16, v8
	v_or_b32_e32 v12, 24, v8
	v_or_b32_e32 v13, 32, v8
	v_or_b32_e32 v14, 40, v8
	v_or_b32_e32 v15, 48, v8
	v_or_b32_e32 v16, 56, v8
	v_add3_u32 v17, v7, v6, 0
	v_add_u32_e32 v18, 0x400, v9

.LBB0_59:
	s_or_b64 exec, exec, s[10:11]
	s_mov_b64 s[4:5], s[0:1]
	s_mov_b64 s[10:11], s[0:1]
	v_mov_b32_e32 v6, v190
	s_nop 0
	v_readfirstlane_b32 s3, v6
	s_ashr_i32 s7, s3, 6
	s_mov_b32 s3, s2
	s_lshl_b32 s3, s3, 3
	s_add_i32 s3, s3, s7
	s_cmp_eq_u32 s24, 0x100
	s_cbranch_scc0 .Lp0rot_6
	s_add_i32 s3, s3, 1216
	s_and_b32 s3, s3, 0x7ff
.Lp0rot_6:
	s_cmpk_gt_i32 s3, 0x7f
	s_cbranch_scc1 .LBB0_64
	s_load_dwordx2 s[12:13], s[4:5], 0x50
	s_load_dwordx2 s[14:15], s[10:11], 0xe0
	v_lshlrev_b32_e32 v2, 4, v6
	v_and_b32_e32 v4, 0xf0, v2
	v_mov_b32_e32 v5, 0
	s_waitcnt lgkmcnt(0)
	v_lshl_add_u64 v[2:3], s[12:13], 0, v[4:5]
	v_lshlrev_b32_e32 v4, 3, v6
	s_mulk_i32 s7, 0x4100
	v_bfe_u32 v8, v6, 3, 3
	v_and_b32_e32 v4, 56, v4
	s_add_i32 s9, s7, 0
	v_mul_u32_u24_e32 v7, 0x104, v4
	v_lshlrev_b32_e32 v9, 2, v8
	v_bfe_u32 v1, v6, 4, 2
	s_movk_i32 s10, 0x104
	v_lshlrev_b32_e32 v4, 1, v4
	v_add3_u32 v9, s9, v7, v9
	v_mov_b32_e32 v7, s7
	v_and_b32_e32 v6, 15, v6
	v_lshl_add_u64 v[4:5], s[14:15], 0, v[4:5]
	s_mov_b64 s[4:5], 0x1e00000
	v_mad_u32_u24 v7, v1, s10, v7
	v_lshlrev_b32_e32 v6, 4, v6
	v_lshl_add_u64 v[4:5], v[4:5], 0, s[4:5]
	v_or_b32_e32 v10, 8, v8
	v_or_b32_e32 v11, 16, v8
	v_or_b32_e32 v12, 24, v8
	v_or_b32_e32 v13, 32, v8
	v_or_b32_e32 v14, 40, v8
	v_or_b32_e32 v15, 48, v8
	v_or_b32_e32 v16, 56, v8
	v_add3_u32 v17, v7, v6, 0
	v_add_u32_e32 v18, 0x400, v9
